# grid barrier: the XCD generation word is no longer bumped (nobody polls it), so barrier leaders skip that atomic and its completion wait
# baseline (speedup 1.0000x reference)
.LBB0_218:
	s_or_b64 exec, exec, s[4:5]
	s_mov_b64 s[4:5], exec
	v_mbcnt_lo_u32_b32 v0, s4, 0
	v_mbcnt_hi_u32_b32 v0, s5, v0
	v_cmp_eq_u32_e32 vcc, 0, v0
	s_waitcnt vmcnt(0)
	buffer_inv sc1
	s_and_saveexec_b64 s[6:7], vcc
	s_cbranch_execz .LBB0_220
	s_bcnt1_i32_b64 s4, s[4:5]
	v_mov_b32_e32 v0, s4
	v_readlane_b32 s4, v252, 54
	v_readlane_b32 s5, v252, 55
	s_nop 4
	s_nop 0

.LBB0_1371:
	s_or_b64 exec, exec, s[4:5]
	s_mov_b64 s[4:5], exec
	v_mbcnt_lo_u32_b32 v0, s4, 0
	v_mbcnt_hi_u32_b32 v0, s5, v0
	v_cmp_eq_u32_e32 vcc, 0, v0
	s_waitcnt vmcnt(0)
	buffer_inv sc1
	s_and_saveexec_b64 s[8:9], vcc
	s_cbranch_execz .LBB0_1373
	s_bcnt1_i32_b64 s4, s[4:5]
	v_mov_b32_e32 v0, s4
	v_readlane_b32 s4, v252, 54
	v_readlane_b32 s5, v252, 55
	s_nop 4
	s_nop 0

.LBB0_1676:
	s_bcnt1_i32_b64 s4, s[4:5]
	v_mov_b32_e32 v0, s4
	v_readlane_b32 s4, v252, 54
	v_readlane_b32 s5, v252, 55
	s_nop 4
	s_nop 0
	s_getpc_b64 s[98:99]
